# hyena_filters w3 GEMV inner loop software pipelined (next k-step global loads and LDS broadcast reads prefetched, unroll x2)
# speedup vs baseline: 1.0194x; 1.0083x over previous
.LBB0_958:
	global_load_dwordx4 v[0:3], v[20:21], off
	global_load_dwordx4 v[178:181], v[20:21], off offset:-16
	v_add_u32_e64 v29, 64, s0
	ds_read2st64_b32 v[222:223], v29 offset0:24 offset1:25
	ds_read2st64_b32 v[224:225], v29 offset0:26 offset1:27
	ds_read2st64_b32 v[226:227], v29 offset0:28 offset1:29
	ds_read2st64_b32 v[228:229], v29 offset0:30 offset1:31
	ds_read2st64_b32 v[230:231], v29 offset0:32 offset1:33
	ds_read2st64_b32 v[232:233], v29 offset0:34 offset1:35
	ds_read2st64_b32 v[234:235], v29 offset0:36 offset1:37
	ds_read2st64_b32 v[236:237], v29 offset0:38 offset1:39
	s_movk_i32 s0, 31
.Lhf_loop:
	s_waitcnt lgkmcnt(0)
	v_lshl_add_u64 v[20:21], v[20:21], 0, s[16:17]
	global_load_dwordx4 v[182:185], v[20:21], off
	global_load_dwordx4 v[186:189], v[20:21], off offset:-16
	v_add_u32_e32 v193, 4, v29
	ds_read2st64_b32 v[238:239], v193 offset0:24 offset1:25
	ds_read2st64_b32 v[240:241], v193 offset0:26 offset1:27
	ds_read2st64_b32 v[242:243], v193 offset0:28 offset1:29
	ds_read2st64_b32 v[244:245], v193 offset0:30 offset1:31
	ds_read2st64_b32 v[246:247], v193 offset0:32 offset1:33
	ds_read2st64_b32 v[248:249], v193 offset0:34 offset1:35
	ds_read2st64_b32 v[250:251], v193 offset0:36 offset1:37
	ds_read2st64_b32 v[24:25], v193 offset0:38 offset1:39
	s_waitcnt vmcnt(2)
	v_mov_b32_e32 v164, v3
	v_mov_b32_e32 v28, v181
	v_pk_fma_f32 v[4:5], v[178:179], v[222:223], v[4:5] op_sel_hi:[0,1,1]
	v_pk_fma_f32 v[22:23], v[222:223], v[0:1], v[22:23] op_sel_hi:[1,0,1]
	v_pk_fma_f32 v[8:9], v[178:179], v[222:223], v[8:9] op_sel:[1,0,0]
	v_pk_fma_f32 v[30:31], v[222:223], v[0:1], v[30:31] op_sel:[0,1,0]
	v_pk_fma_f32 v[12:13], v[180:181], v[222:223], v[12:13] op_sel_hi:[0,1,1]
	v_pk_fma_f32 v[26:27], v[222:223], v[2:3], v[26:27] op_sel_hi:[1,0,1]
	v_pk_fma_f32 v[16:17], v[28:29], v[222:223], v[16:17] op_sel_hi:[0,1,1]
	v_pk_fma_f32 v[176:177], v[222:223], v[164:165], v[176:177] op_sel_hi:[1,0,1]
	v_pk_fma_f32 v[6:7], v[178:179], v[224:225], v[6:7] op_sel_hi:[0,1,1]
	v_pk_fma_f32 v[58:59], v[0:1], v[224:225], v[58:59] op_sel_hi:[0,1,1]
	v_pk_fma_f32 v[10:11], v[178:179], v[224:225], v[10:11] op_sel:[1,0,0]
	v_pk_fma_f32 v[62:63], v[0:1], v[224:225], v[62:63] op_sel:[1,0,0]
	v_pk_fma_f32 v[14:15], v[180:181], v[224:225], v[14:15] op_sel_hi:[0,1,1]
	v_pk_fma_f32 v[60:61], v[2:3], v[224:225], v[60:61] op_sel_hi:[0,1,1]
	v_pk_fma_f32 v[18:19], v[28:29], v[224:225], v[18:19] op_sel_hi:[0,1,1]
	v_pk_fma_f32 v[92:93], v[164:165], v[224:225], v[92:93] op_sel_hi:[0,1,1]
	v_pk_fma_f32 v[44:45], v[178:179], v[226:227], v[44:45] op_sel_hi:[0,1,1]
	v_pk_fma_f32 v[36:37], v[0:1], v[226:227], v[36:37] op_sel_hi:[0,1,1]
	v_pk_fma_f32 v[56:57], v[178:179], v[226:227], v[56:57] op_sel:[1,0,0]
	v_pk_fma_f32 v[48:49], v[0:1], v[226:227], v[48:49] op_sel:[1,0,0]
	v_pk_fma_f32 v[40:41], v[180:181], v[226:227], v[40:41] op_sel_hi:[0,1,1]
	v_pk_fma_f32 v[32:33], v[2:3], v[226:227], v[32:33] op_sel_hi:[0,1,1]
	v_pk_fma_f32 v[52:53], v[28:29], v[226:227], v[52:53] op_sel_hi:[0,1,1]
	v_pk_fma_f32 v[46:47], v[164:165], v[226:227], v[46:47] op_sel_hi:[0,1,1]
	v_pk_fma_f32 v[34:35], v[178:179], v[228:229], v[34:35] op_sel_hi:[0,1,1]
	v_pk_fma_f32 v[54:55], v[0:1], v[228:229], v[54:55] op_sel_hi:[0,1,1]
	v_pk_fma_f32 v[38:39], v[178:179], v[228:229], v[38:39] op_sel:[1,0,0]
	v_pk_fma_f32 v[84:85], v[0:1], v[228:229], v[84:85] op_sel:[1,0,0]
	v_pk_fma_f32 v[42:43], v[180:181], v[228:229], v[42:43] op_sel_hi:[0,1,1]
	v_pk_fma_f32 v[80:81], v[2:3], v[228:229], v[80:81] op_sel_hi:[0,1,1]
	v_pk_fma_f32 v[50:51], v[28:29], v[228:229], v[50:51] op_sel_hi:[0,1,1]
	v_pk_fma_f32 v[88:89], v[164:165], v[228:229], v[88:89] op_sel_hi:[0,1,1]
	v_pk_fma_f32 v[64:65], v[178:179], v[230:231], v[64:65] op_sel_hi:[0,1,1]
	v_pk_fma_f32 v[82:83], v[0:1], v[230:231], v[82:83] op_sel_hi:[0,1,1]
	v_pk_fma_f32 v[68:69], v[178:179], v[230:231], v[68:69] op_sel:[1,0,0]
	v_pk_fma_f32 v[90:91], v[0:1], v[230:231], v[90:91] op_sel:[1,0,0]
	v_pk_fma_f32 v[72:73], v[180:181], v[230:231], v[72:73] op_sel_hi:[0,1,1]
	v_pk_fma_f32 v[86:87], v[2:3], v[230:231], v[86:87] op_sel_hi:[0,1,1]
	v_pk_fma_f32 v[76:77], v[28:29], v[230:231], v[76:77] op_sel_hi:[0,1,1]
	v_pk_fma_f32 v[94:95], v[164:165], v[230:231], v[94:95] op_sel_hi:[0,1,1]
	v_pk_fma_f32 v[66:67], v[178:179], v[232:233], v[66:67] op_sel_hi:[0,1,1]
	v_pk_fma_f32 v[114:115], v[0:1], v[232:233], v[114:115] op_sel_hi:[0,1,1]
	v_pk_fma_f32 v[70:71], v[178:179], v[232:233], v[70:71] op_sel:[1,0,0]
	v_pk_fma_f32 v[122:123], v[0:1], v[232:233], v[122:123] op_sel:[1,0,0]
	v_pk_fma_f32 v[74:75], v[180:181], v[232:233], v[74:75] op_sel_hi:[0,1,1]
	v_pk_fma_f32 v[118:119], v[2:3], v[232:233], v[118:119] op_sel_hi:[0,1,1]
	v_pk_fma_f32 v[78:79], v[28:29], v[232:233], v[78:79] op_sel_hi:[0,1,1]
	v_pk_fma_f32 v[126:127], v[164:165], v[232:233], v[126:127] op_sel_hi:[0,1,1]
	v_pk_fma_f32 v[96:97], v[178:179], v[234:235], v[96:97] op_sel_hi:[0,1,1]
	v_pk_fma_f32 v[128:129], v[0:1], v[234:235], v[128:129] op_sel_hi:[0,1,1]
	v_pk_fma_f32 v[100:101], v[178:179], v[234:235], v[100:101] op_sel:[1,0,0]
	v_pk_fma_f32 v[132:133], v[0:1], v[234:235], v[132:133] op_sel:[1,0,0]
	v_pk_fma_f32 v[104:105], v[180:181], v[234:235], v[104:105] op_sel_hi:[0,1,1]
	v_pk_fma_f32 v[130:131], v[2:3], v[234:235], v[130:131] op_sel_hi:[0,1,1]
	v_pk_fma_f32 v[108:109], v[28:29], v[234:235], v[108:109] op_sel_hi:[0,1,1]
	v_pk_fma_f32 v[134:135], v[164:165], v[234:235], v[134:135] op_sel_hi:[0,1,1]
	v_pk_fma_f32 v[120:121], v[178:179], v[236:237], v[120:121] op_sel_hi:[0,1,1]
	v_pk_fma_f32 v[102:103], v[0:1], v[236:237], v[102:103] op_sel_hi:[0,1,1]
	v_pk_fma_f32 v[124:125], v[178:179], v[236:237], v[124:125] op_sel:[1,0,0]
	v_pk_fma_f32 v[106:107], v[0:1], v[236:237], v[106:107] op_sel:[1,0,0]
	v_pk_fma_f32 v[110:111], v[180:181], v[236:237], v[110:111] op_sel_hi:[0,1,1]
	v_pk_fma_f32 v[98:99], v[2:3], v[236:237], v[98:99] op_sel_hi:[0,1,1]
	v_pk_fma_f32 v[116:117], v[28:29], v[236:237], v[116:117] op_sel_hi:[0,1,1]
	v_pk_fma_f32 v[136:137], v[164:165], v[236:237], v[136:137] op_sel_hi:[0,1,1]
	s_waitcnt lgkmcnt(0)
	v_lshl_add_u64 v[20:21], v[20:21], 0, s[16:17]
	global_load_dwordx4 v[0:3], v[20:21], off
	global_load_dwordx4 v[178:181], v[20:21], off offset:-16
	v_add_u32_e32 v29, 8, v29
	ds_read2st64_b32 v[222:223], v29 offset0:24 offset1:25
	ds_read2st64_b32 v[224:225], v29 offset0:26 offset1:27
	ds_read2st64_b32 v[226:227], v29 offset0:28 offset1:29
	ds_read2st64_b32 v[228:229], v29 offset0:30 offset1:31
	ds_read2st64_b32 v[230:231], v29 offset0:32 offset1:33
	ds_read2st64_b32 v[232:233], v29 offset0:34 offset1:35
	ds_read2st64_b32 v[234:235], v29 offset0:36 offset1:37
	ds_read2st64_b32 v[236:237], v29 offset0:38 offset1:39
	s_waitcnt vmcnt(2)
	v_mov_b32_e32 v190, v185
	v_mov_b32_e32 v194, v189
	v_pk_fma_f32 v[4:5], v[186:187], v[238:239], v[4:5] op_sel_hi:[0,1,1]
	v_pk_fma_f32 v[22:23], v[238:239], v[182:183], v[22:23] op_sel_hi:[1,0,1]
	v_pk_fma_f32 v[8:9], v[186:187], v[238:239], v[8:9] op_sel:[1,0,0]
	v_pk_fma_f32 v[30:31], v[238:239], v[182:183], v[30:31] op_sel:[0,1,0]
	v_pk_fma_f32 v[12:13], v[188:189], v[238:239], v[12:13] op_sel_hi:[0,1,1]
	v_pk_fma_f32 v[26:27], v[238:239], v[184:185], v[26:27] op_sel_hi:[1,0,1]
	v_pk_fma_f32 v[16:17], v[194:195], v[238:239], v[16:17] op_sel_hi:[0,1,1]
	v_pk_fma_f32 v[176:177], v[238:239], v[190:191], v[176:177] op_sel_hi:[1,0,1]
	v_pk_fma_f32 v[6:7], v[186:187], v[240:241], v[6:7] op_sel_hi:[0,1,1]
	v_pk_fma_f32 v[58:59], v[182:183], v[240:241], v[58:59] op_sel_hi:[0,1,1]
	v_pk_fma_f32 v[10:11], v[186:187], v[240:241], v[10:11] op_sel:[1,0,0]
	v_pk_fma_f32 v[62:63], v[182:183], v[240:241], v[62:63] op_sel:[1,0,0]
	v_pk_fma_f32 v[14:15], v[188:189], v[240:241], v[14:15] op_sel_hi:[0,1,1]
	v_pk_fma_f32 v[60:61], v[184:185], v[240:241], v[60:61] op_sel_hi:[0,1,1]
	v_pk_fma_f32 v[18:19], v[194:195], v[240:241], v[18:19] op_sel_hi:[0,1,1]
	v_pk_fma_f32 v[92:93], v[190:191], v[240:241], v[92:93] op_sel_hi:[0,1,1]
	v_pk_fma_f32 v[44:45], v[186:187], v[242:243], v[44:45] op_sel_hi:[0,1,1]
	v_pk_fma_f32 v[36:37], v[182:183], v[242:243], v[36:37] op_sel_hi:[0,1,1]
	v_pk_fma_f32 v[56:57], v[186:187], v[242:243], v[56:57] op_sel:[1,0,0]
	v_pk_fma_f32 v[48:49], v[182:183], v[242:243], v[48:49] op_sel:[1,0,0]
	v_pk_fma_f32 v[40:41], v[188:189], v[242:243], v[40:41] op_sel_hi:[0,1,1]
	v_pk_fma_f32 v[32:33], v[184:185], v[242:243], v[32:33] op_sel_hi:[0,1,1]
	v_pk_fma_f32 v[52:53], v[194:195], v[242:243], v[52:53] op_sel_hi:[0,1,1]
	v_pk_fma_f32 v[46:47], v[190:191], v[242:243], v[46:47] op_sel_hi:[0,1,1]
	v_pk_fma_f32 v[34:35], v[186:187], v[244:245], v[34:35] op_sel_hi:[0,1,1]
	v_pk_fma_f32 v[54:55], v[182:183], v[244:245], v[54:55] op_sel_hi:[0,1,1]
	v_pk_fma_f32 v[38:39], v[186:187], v[244:245], v[38:39] op_sel:[1,0,0]
	v_pk_fma_f32 v[84:85], v[182:183], v[244:245], v[84:85] op_sel:[1,0,0]
	v_pk_fma_f32 v[42:43], v[188:189], v[244:245], v[42:43] op_sel_hi:[0,1,1]
	v_pk_fma_f32 v[80:81], v[184:185], v[244:245], v[80:81] op_sel_hi:[0,1,1]
	v_pk_fma_f32 v[50:51], v[194:195], v[244:245], v[50:51] op_sel_hi:[0,1,1]
	v_pk_fma_f32 v[88:89], v[190:191], v[244:245], v[88:89] op_sel_hi:[0,1,1]
	v_pk_fma_f32 v[64:65], v[186:187], v[246:247], v[64:65] op_sel_hi:[0,1,1]
	v_pk_fma_f32 v[82:83], v[182:183], v[246:247], v[82:83] op_sel_hi:[0,1,1]
	v_pk_fma_f32 v[68:69], v[186:187], v[246:247], v[68:69] op_sel:[1,0,0]
	v_pk_fma_f32 v[90:91], v[182:183], v[246:247], v[90:91] op_sel:[1,0,0]
	v_pk_fma_f32 v[72:73], v[188:189], v[246:247], v[72:73] op_sel_hi:[0,1,1]
	v_pk_fma_f32 v[86:87], v[184:185], v[246:247], v[86:87] op_sel_hi:[0,1,1]
	v_pk_fma_f32 v[76:77], v[194:195], v[246:247], v[76:77] op_sel_hi:[0,1,1]
	v_pk_fma_f32 v[94:95], v[190:191], v[246:247], v[94:95] op_sel_hi:[0,1,1]
	v_pk_fma_f32 v[66:67], v[186:187], v[248:249], v[66:67] op_sel_hi:[0,1,1]
	v_pk_fma_f32 v[114:115], v[182:183], v[248:249], v[114:115] op_sel_hi:[0,1,1]
	v_pk_fma_f32 v[70:71], v[186:187], v[248:249], v[70:71] op_sel:[1,0,0]
	v_pk_fma_f32 v[122:123], v[182:183], v[248:249], v[122:123] op_sel:[1,0,0]
	v_pk_fma_f32 v[74:75], v[188:189], v[248:249], v[74:75] op_sel_hi:[0,1,1]
	v_pk_fma_f32 v[118:119], v[184:185], v[248:249], v[118:119] op_sel_hi:[0,1,1]
	v_pk_fma_f32 v[78:79], v[194:195], v[248:249], v[78:79] op_sel_hi:[0,1,1]
	v_pk_fma_f32 v[126:127], v[190:191], v[248:249], v[126:127] op_sel_hi:[0,1,1]
	v_pk_fma_f32 v[96:97], v[186:187], v[250:251], v[96:97] op_sel_hi:[0,1,1]
	v_pk_fma_f32 v[128:129], v[182:183], v[250:251], v[128:129] op_sel_hi:[0,1,1]
	v_pk_fma_f32 v[100:101], v[186:187], v[250:251], v[100:101] op_sel:[1,0,0]
	v_pk_fma_f32 v[132:133], v[182:183], v[250:251], v[132:133] op_sel:[1,0,0]
	v_pk_fma_f32 v[104:105], v[188:189], v[250:251], v[104:105] op_sel_hi:[0,1,1]
	v_pk_fma_f32 v[130:131], v[184:185], v[250:251], v[130:131] op_sel_hi:[0,1,1]
	v_pk_fma_f32 v[108:109], v[194:195], v[250:251], v[108:109] op_sel_hi:[0,1,1]
	v_pk_fma_f32 v[134:135], v[190:191], v[250:251], v[134:135] op_sel_hi:[0,1,1]
	v_pk_fma_f32 v[120:121], v[186:187], v[24:25], v[120:121] op_sel_hi:[0,1,1]
	v_pk_fma_f32 v[102:103], v[182:183], v[24:25], v[102:103] op_sel_hi:[0,1,1]
	v_pk_fma_f32 v[124:125], v[186:187], v[24:25], v[124:125] op_sel:[1,0,0]
	v_pk_fma_f32 v[106:107], v[182:183], v[24:25], v[106:107] op_sel:[1,0,0]
	v_pk_fma_f32 v[110:111], v[188:189], v[24:25], v[110:111] op_sel_hi:[0,1,1]
	v_pk_fma_f32 v[98:99], v[184:185], v[24:25], v[98:99] op_sel_hi:[0,1,1]
	v_pk_fma_f32 v[116:117], v[194:195], v[24:25], v[116:117] op_sel_hi:[0,1,1]
	v_pk_fma_f32 v[136:137], v[190:191], v[24:25], v[136:137] op_sel_hi:[0,1,1]
	s_add_i32 s0, s0, -1
	s_cmp_lg_u32 s0, 0
	s_cbranch_scc1 .Lhf_loop
	s_waitcnt lgkmcnt(0)
	v_lshl_add_u64 v[20:21], v[20:21], 0, s[16:17]
	global_load_dwordx4 v[182:185], v[20:21], off
	global_load_dwordx4 v[186:189], v[20:21], off offset:-16
	v_add_u32_e32 v193, 4, v29
	ds_read2st64_b32 v[238:239], v193 offset0:24 offset1:25
	ds_read2st64_b32 v[240:241], v193 offset0:26 offset1:27
	ds_read2st64_b32 v[242:243], v193 offset0:28 offset1:29
	ds_read2st64_b32 v[244:245], v193 offset0:30 offset1:31
	ds_read2st64_b32 v[246:247], v193 offset0:32 offset1:33
	ds_read2st64_b32 v[248:249], v193 offset0:34 offset1:35
	ds_read2st64_b32 v[250:251], v193 offset0:36 offset1:37
	ds_read2st64_b32 v[24:25], v193 offset0:38 offset1:39
	s_waitcnt vmcnt(2)
	v_mov_b32_e32 v164, v3
	v_mov_b32_e32 v28, v181
	v_pk_fma_f32 v[4:5], v[178:179], v[222:223], v[4:5] op_sel_hi:[0,1,1]
	v_pk_fma_f32 v[22:23], v[222:223], v[0:1], v[22:23] op_sel_hi:[1,0,1]
	v_pk_fma_f32 v[8:9], v[178:179], v[222:223], v[8:9] op_sel:[1,0,0]
	v_pk_fma_f32 v[30:31], v[222:223], v[0:1], v[30:31] op_sel:[0,1,0]
	v_pk_fma_f32 v[12:13], v[180:181], v[222:223], v[12:13] op_sel_hi:[0,1,1]
	v_pk_fma_f32 v[26:27], v[222:223], v[2:3], v[26:27] op_sel_hi:[1,0,1]
	v_pk_fma_f32 v[16:17], v[28:29], v[222:223], v[16:17] op_sel_hi:[0,1,1]
	v_pk_fma_f32 v[176:177], v[222:223], v[164:165], v[176:177] op_sel_hi:[1,0,1]
	v_pk_fma_f32 v[6:7], v[178:179], v[224:225], v[6:7] op_sel_hi:[0,1,1]
	v_pk_fma_f32 v[58:59], v[0:1], v[224:225], v[58:59] op_sel_hi:[0,1,1]
	v_pk_fma_f32 v[10:11], v[178:179], v[224:225], v[10:11] op_sel:[1,0,0]
	v_pk_fma_f32 v[62:63], v[0:1], v[224:225], v[62:63] op_sel:[1,0,0]
	v_pk_fma_f32 v[14:15], v[180:181], v[224:225], v[14:15] op_sel_hi:[0,1,1]
	v_pk_fma_f32 v[60:61], v[2:3], v[224:225], v[60:61] op_sel_hi:[0,1,1]
	v_pk_fma_f32 v[18:19], v[28:29], v[224:225], v[18:19] op_sel_hi:[0,1,1]
	v_pk_fma_f32 v[92:93], v[164:165], v[224:225], v[92:93] op_sel_hi:[0,1,1]
	v_pk_fma_f32 v[44:45], v[178:179], v[226:227], v[44:45] op_sel_hi:[0,1,1]
	v_pk_fma_f32 v[36:37], v[0:1], v[226:227], v[36:37] op_sel_hi:[0,1,1]
	v_pk_fma_f32 v[56:57], v[178:179], v[226:227], v[56:57] op_sel:[1,0,0]
	v_pk_fma_f32 v[48:49], v[0:1], v[226:227], v[48:49] op_sel:[1,0,0]
	v_pk_fma_f32 v[40:41], v[180:181], v[226:227], v[40:41] op_sel_hi:[0,1,1]
	v_pk_fma_f32 v[32:33], v[2:3], v[226:227], v[32:33] op_sel_hi:[0,1,1]
	v_pk_fma_f32 v[52:53], v[28:29], v[226:227], v[52:53] op_sel_hi:[0,1,1]
	v_pk_fma_f32 v[46:47], v[164:165], v[226:227], v[46:47] op_sel_hi:[0,1,1]
	v_pk_fma_f32 v[34:35], v[178:179], v[228:229], v[34:35] op_sel_hi:[0,1,1]
	v_pk_fma_f32 v[54:55], v[0:1], v[228:229], v[54:55] op_sel_hi:[0,1,1]
	v_pk_fma_f32 v[38:39], v[178:179], v[228:229], v[38:39] op_sel:[1,0,0]
	v_pk_fma_f32 v[84:85], v[0:1], v[228:229], v[84:85] op_sel:[1,0,0]
	v_pk_fma_f32 v[42:43], v[180:181], v[228:229], v[42:43] op_sel_hi:[0,1,1]
	v_pk_fma_f32 v[80:81], v[2:3], v[228:229], v[80:81] op_sel_hi:[0,1,1]
	v_pk_fma_f32 v[50:51], v[28:29], v[228:229], v[50:51] op_sel_hi:[0,1,1]
	v_pk_fma_f32 v[88:89], v[164:165], v[228:229], v[88:89] op_sel_hi:[0,1,1]
	v_pk_fma_f32 v[64:65], v[178:179], v[230:231], v[64:65] op_sel_hi:[0,1,1]
	v_pk_fma_f32 v[82:83], v[0:1], v[230:231], v[82:83] op_sel_hi:[0,1,1]
	v_pk_fma_f32 v[68:69], v[178:179], v[230:231], v[68:69] op_sel:[1,0,0]
	v_pk_fma_f32 v[90:91], v[0:1], v[230:231], v[90:91] op_sel:[1,0,0]
	v_pk_fma_f32 v[72:73], v[180:181], v[230:231], v[72:73] op_sel_hi:[0,1,1]
	v_pk_fma_f32 v[86:87], v[2:3], v[230:231], v[86:87] op_sel_hi:[0,1,1]
	v_pk_fma_f32 v[76:77], v[28:29], v[230:231], v[76:77] op_sel_hi:[0,1,1]
	v_pk_fma_f32 v[94:95], v[164:165], v[230:231], v[94:95] op_sel_hi:[0,1,1]
	v_pk_fma_f32 v[66:67], v[178:179], v[232:233], v[66:67] op_sel_hi:[0,1,1]
	v_pk_fma_f32 v[114:115], v[0:1], v[232:233], v[114:115] op_sel_hi:[0,1,1]
	v_pk_fma_f32 v[70:71], v[178:179], v[232:233], v[70:71] op_sel:[1,0,0]
	v_pk_fma_f32 v[122:123], v[0:1], v[232:233], v[122:123] op_sel:[1,0,0]
	v_pk_fma_f32 v[74:75], v[180:181], v[232:233], v[74:75] op_sel_hi:[0,1,1]
	v_pk_fma_f32 v[118:119], v[2:3], v[232:233], v[118:119] op_sel_hi:[0,1,1]
	v_pk_fma_f32 v[78:79], v[28:29], v[232:233], v[78:79] op_sel_hi:[0,1,1]
	v_pk_fma_f32 v[126:127], v[164:165], v[232:233], v[126:127] op_sel_hi:[0,1,1]
	v_pk_fma_f32 v[96:97], v[178:179], v[234:235], v[96:97] op_sel_hi:[0,1,1]
	v_pk_fma_f32 v[128:129], v[0:1], v[234:235], v[128:129] op_sel_hi:[0,1,1]
	v_pk_fma_f32 v[100:101], v[178:179], v[234:235], v[100:101] op_sel:[1,0,0]
	v_pk_fma_f32 v[132:133], v[0:1], v[234:235], v[132:133] op_sel:[1,0,0]
	v_pk_fma_f32 v[104:105], v[180:181], v[234:235], v[104:105] op_sel_hi:[0,1,1]
	v_pk_fma_f32 v[130:131], v[2:3], v[234:235], v[130:131] op_sel_hi:[0,1,1]
	v_pk_fma_f32 v[108:109], v[28:29], v[234:235], v[108:109] op_sel_hi:[0,1,1]
	v_pk_fma_f32 v[134:135], v[164:165], v[234:235], v[134:135] op_sel_hi:[0,1,1]
	v_pk_fma_f32 v[120:121], v[178:179], v[236:237], v[120:121] op_sel_hi:[0,1,1]
	v_pk_fma_f32 v[102:103], v[0:1], v[236:237], v[102:103] op_sel_hi:[0,1,1]
	v_pk_fma_f32 v[124:125], v[178:179], v[236:237], v[124:125] op_sel:[1,0,0]
	v_pk_fma_f32 v[106:107], v[0:1], v[236:237], v[106:107] op_sel:[1,0,0]
	v_pk_fma_f32 v[110:111], v[180:181], v[236:237], v[110:111] op_sel_hi:[0,1,1]
	v_pk_fma_f32 v[98:99], v[2:3], v[236:237], v[98:99] op_sel_hi:[0,1,1]
	v_pk_fma_f32 v[116:117], v[28:29], v[236:237], v[116:117] op_sel_hi:[0,1,1]
	v_pk_fma_f32 v[136:137], v[164:165], v[236:237], v[136:137] op_sel_hi:[0,1,1]
	s_waitcnt lgkmcnt(0)
	s_waitcnt vmcnt(0)
	v_mov_b32_e32 v190, v185
	v_mov_b32_e32 v194, v189
	v_pk_fma_f32 v[4:5], v[186:187], v[238:239], v[4:5] op_sel_hi:[0,1,1]
	v_pk_fma_f32 v[22:23], v[238:239], v[182:183], v[22:23] op_sel_hi:[1,0,1]
	v_pk_fma_f32 v[8:9], v[186:187], v[238:239], v[8:9] op_sel:[1,0,0]
	v_pk_fma_f32 v[30:31], v[238:239], v[182:183], v[30:31] op_sel:[0,1,0]
	v_pk_fma_f32 v[12:13], v[188:189], v[238:239], v[12:13] op_sel_hi:[0,1,1]
	v_pk_fma_f32 v[26:27], v[238:239], v[184:185], v[26:27] op_sel_hi:[1,0,1]
	v_pk_fma_f32 v[16:17], v[194:195], v[238:239], v[16:17] op_sel_hi:[0,1,1]
	v_pk_fma_f32 v[176:177], v[238:239], v[190:191], v[176:177] op_sel_hi:[1,0,1]
	v_pk_fma_f32 v[6:7], v[186:187], v[240:241], v[6:7] op_sel_hi:[0,1,1]
	v_pk_fma_f32 v[58:59], v[182:183], v[240:241], v[58:59] op_sel_hi:[0,1,1]
	v_pk_fma_f32 v[10:11], v[186:187], v[240:241], v[10:11] op_sel:[1,0,0]
	v_pk_fma_f32 v[62:63], v[182:183], v[240:241], v[62:63] op_sel:[1,0,0]
	v_pk_fma_f32 v[14:15], v[188:189], v[240:241], v[14:15] op_sel_hi:[0,1,1]
	v_pk_fma_f32 v[60:61], v[184:185], v[240:241], v[60:61] op_sel_hi:[0,1,1]
	v_pk_fma_f32 v[18:19], v[194:195], v[240:241], v[18:19] op_sel_hi:[0,1,1]
	v_pk_fma_f32 v[92:93], v[190:191], v[240:241], v[92:93] op_sel_hi:[0,1,1]
	v_pk_fma_f32 v[44:45], v[186:187], v[242:243], v[44:45] op_sel_hi:[0,1,1]
	v_pk_fma_f32 v[36:37], v[182:183], v[242:243], v[36:37] op_sel_hi:[0,1,1]
	v_pk_fma_f32 v[56:57], v[186:187], v[242:243], v[56:57] op_sel:[1,0,0]
	v_pk_fma_f32 v[48:49], v[182:183], v[242:243], v[48:49] op_sel:[1,0,0]
	v_pk_fma_f32 v[40:41], v[188:189], v[242:243], v[40:41] op_sel_hi:[0,1,1]
	v_pk_fma_f32 v[32:33], v[184:185], v[242:243], v[32:33] op_sel_hi:[0,1,1]
	v_pk_fma_f32 v[52:53], v[194:195], v[242:243], v[52:53] op_sel_hi:[0,1,1]
	v_pk_fma_f32 v[46:47], v[190:191], v[242:243], v[46:47] op_sel_hi:[0,1,1]
	v_pk_fma_f32 v[34:35], v[186:187], v[244:245], v[34:35] op_sel_hi:[0,1,1]
	v_pk_fma_f32 v[54:55], v[182:183], v[244:245], v[54:55] op_sel_hi:[0,1,1]
	v_pk_fma_f32 v[38:39], v[186:187], v[244:245], v[38:39] op_sel:[1,0,0]
	v_pk_fma_f32 v[84:85], v[182:183], v[244:245], v[84:85] op_sel:[1,0,0]
	v_pk_fma_f32 v[42:43], v[188:189], v[244:245], v[42:43] op_sel_hi:[0,1,1]
	v_pk_fma_f32 v[80:81], v[184:185], v[244:245], v[80:81] op_sel_hi:[0,1,1]
	v_pk_fma_f32 v[50:51], v[194:195], v[244:245], v[50:51] op_sel_hi:[0,1,1]
	v_pk_fma_f32 v[88:89], v[190:191], v[244:245], v[88:89] op_sel_hi:[0,1,1]
	v_pk_fma_f32 v[64:65], v[186:187], v[246:247], v[64:65] op_sel_hi:[0,1,1]
	v_pk_fma_f32 v[82:83], v[182:183], v[246:247], v[82:83] op_sel_hi:[0,1,1]
	v_pk_fma_f32 v[68:69], v[186:187], v[246:247], v[68:69] op_sel:[1,0,0]
	v_pk_fma_f32 v[90:91], v[182:183], v[246:247], v[90:91] op_sel:[1,0,0]
	v_pk_fma_f32 v[72:73], v[188:189], v[246:247], v[72:73] op_sel_hi:[0,1,1]
	v_pk_fma_f32 v[86:87], v[184:185], v[246:247], v[86:87] op_sel_hi:[0,1,1]
	v_pk_fma_f32 v[76:77], v[194:195], v[246:247], v[76:77] op_sel_hi:[0,1,1]
	v_pk_fma_f32 v[94:95], v[190:191], v[246:247], v[94:95] op_sel_hi:[0,1,1]
	v_pk_fma_f32 v[66:67], v[186:187], v[248:249], v[66:67] op_sel_hi:[0,1,1]
	v_pk_fma_f32 v[114:115], v[182:183], v[248:249], v[114:115] op_sel_hi:[0,1,1]
	v_pk_fma_f32 v[70:71], v[186:187], v[248:249], v[70:71] op_sel:[1,0,0]
	v_pk_fma_f32 v[122:123], v[182:183], v[248:249], v[122:123] op_sel:[1,0,0]
	v_pk_fma_f32 v[74:75], v[188:189], v[248:249], v[74:75] op_sel_hi:[0,1,1]
	v_pk_fma_f32 v[118:119], v[184:185], v[248:249], v[118:119] op_sel_hi:[0,1,1]
	v_pk_fma_f32 v[78:79], v[194:195], v[248:249], v[78:79] op_sel_hi:[0,1,1]
	v_pk_fma_f32 v[126:127], v[190:191], v[248:249], v[126:127] op_sel_hi:[0,1,1]
	v_pk_fma_f32 v[96:97], v[186:187], v[250:251], v[96:97] op_sel_hi:[0,1,1]
	v_pk_fma_f32 v[128:129], v[182:183], v[250:251], v[128:129] op_sel_hi:[0,1,1]
	v_pk_fma_f32 v[100:101], v[186:187], v[250:251], v[100:101] op_sel:[1,0,0]
	v_pk_fma_f32 v[132:133], v[182:183], v[250:251], v[132:133] op_sel:[1,0,0]
	v_pk_fma_f32 v[104:105], v[188:189], v[250:251], v[104:105] op_sel_hi:[0,1,1]
	v_pk_fma_f32 v[130:131], v[184:185], v[250:251], v[130:131] op_sel_hi:[0,1,1]
	v_pk_fma_f32 v[108:109], v[194:195], v[250:251], v[108:109] op_sel_hi:[0,1,1]
	v_pk_fma_f32 v[134:135], v[190:191], v[250:251], v[134:135] op_sel_hi:[0,1,1]
	v_pk_fma_f32 v[120:121], v[186:187], v[24:25], v[120:121] op_sel_hi:[0,1,1]
	v_pk_fma_f32 v[102:103], v[182:183], v[24:25], v[102:103] op_sel_hi:[0,1,1]
	v_pk_fma_f32 v[124:125], v[186:187], v[24:25], v[124:125] op_sel:[1,0,0]
	v_pk_fma_f32 v[106:107], v[182:183], v[24:25], v[106:107] op_sel:[1,0,0]
	v_pk_fma_f32 v[110:111], v[188:189], v[24:25], v[110:111] op_sel_hi:[0,1,1]
	v_pk_fma_f32 v[98:99], v[184:185], v[24:25], v[98:99] op_sel_hi:[0,1,1]
	v_pk_fma_f32 v[116:117], v[194:195], v[24:25], v[116:117] op_sel_hi:[0,1,1]
	v_pk_fma_f32 v[136:137], v[190:191], v[24:25], v[136:137] op_sel_hi:[0,1,1]
	s_add_i32 s4, s4, -1
	v_cvt_f32_i32_e32 v0, s14
	v_cvt_f32_u32_e32 v193, s4
	s_mov_b32 s4, 0x3d4ccccd
	v_div_scale_f32 v1, s[0:1], v193, v193, -v0
	v_rcp_f32_e32 v2, v1
	v_div_scale_f32 v3, vcc, -v0, v193, -v0
	s_or_b32 s0, s14, 1
	v_fma_f32 v20, -v1, v2, 1.0
	v_fmac_f32_e32 v2, v20, v2
	v_mul_f32_e32 v20, v3, v2
	v_fma_f32 v21, -v1, v20, v3
	v_fmac_f32_e32 v20, v21, v2
	v_fma_f32 v1, -v1, v20, v3
	v_div_fmas_f32 v1, v1, v2, v20
	v_div_fixup_f32 v3, v1, v193, -v0
	v_mul_f32_e64 v1, |v213|, v3
	v_mul_f32_e32 v1, 0x3fb8aa3b, v1
	v_exp_f32_e32 v2, v1
	v_mul_f32_e64 v1, |v214|, v3
	v_mul_f32_e32 v1, 0x3fb8aa3b, v1
	v_exp_f32_e32 v20, v1
	v_mul_f32_e64 v1, |v215|, v3
	v_mul_f32_e32 v1, 0x3fb8aa3b, v1
	v_exp_f32_e32 v164, v1
	v_mul_f32_e64 v1, |v216|, v3
	v_cvt_f32_i32_e32 v21, s0
	v_mul_f32_e32 v1, 0x3fb8aa3b, v1
	v_exp_f32_e32 v166, v1
	v_mul_f32_e64 v1, |v217|, v3
	v_mul_f32_e32 v1, 0x3fb8aa3b, v1
	v_exp_f32_e32 v178, v1
	v_div_scale_f32 v1, s[0:1], v193, v193, -v21
	v_rcp_f32_e32 v24, v1
	v_mul_f32_e64 v25, |v218|, v3
	v_mul_f32_e32 v25, 0x3fb8aa3b, v25
	v_exp_f32_e32 v180, v25
	v_fma_f32 v25, -v1, v24, 1.0
	v_fmac_f32_e32 v24, v25, v24
	v_div_scale_f32 v25, vcc, -v21, v193, -v21
	v_mul_f32_e32 v28, v25, v24
	v_fma_f32 v29, -v1, v28, v25
	v_fmac_f32_e32 v28, v29, v24
	v_fma_f32 v1, -v1, v28, v25
	v_div_fmas_f32 v1, v1, v24, v28
	v_mul_f32_e64 v0, |v162|, v3
	v_div_fixup_f32 v183, v1, v193, -v21
	v_mul_f32_e64 v3, |v219|, v3
	v_mul_f32_e64 v1, |v162|, v183
	v_mul_f32_e32 v3, 0x3fb8aa3b, v3
	v_mul_f32_e32 v0, 0x3fb8aa3b, v0
	v_mul_f32_e32 v1, 0x3fb8aa3b, v1
	v_exp_f32_e32 v182, v3
	v_mul_f32_e64 v3, |v213|, v183
	v_exp_f32_e32 v0, v0
	v_exp_f32_e32 v1, v1
	v_mul_f32_e32 v3, 0x3fb8aa3b, v3
	v_exp_f32_e32 v3, v3
	v_mul_f32_e64 v21, |v214|, v183
	v_pk_add_f32 v[0:1], v[0:1], s[4:5] op_sel_hi:[1,0]
	v_mul_f32_e32 v21, 0x3fb8aa3b, v21
	v_pk_mul_f32 v[28:29], v[0:1], v[4:5]
	v_pk_add_f32 v[0:1], v[2:3], s[4:5] op_sel_hi:[1,0]
	v_mul_f32_e64 v2, |v215|, v183
	v_mul_f32_e32 v2, 0x3fb8aa3b, v2
	v_exp_f32_e32 v165, v2
	v_mul_f32_e64 v2, |v216|, v183
	v_mul_f32_e32 v2, 0x3fb8aa3b, v2
	v_exp_f32_e32 v21, v21
	v_exp_f32_e32 v167, v2
	v_mul_f32_e64 v2, |v217|, v183
	v_mul_f32_e32 v2, 0x3fb8aa3b, v2
	s_or_b32 s0, s14, 2
	v_exp_f32_e32 v179, v2
	v_mul_f32_e64 v2, |v218|, v183
	v_cvt_f32_i32_e32 v3, s0
	v_mul_f32_e32 v2, 0x3fb8aa3b, v2
	v_pk_mul_f32 v[24:25], v[0:1], v[8:9]
	v_pk_add_f32 v[0:1], v[20:21], s[4:5] op_sel_hi:[1,0]
	v_exp_f32_e32 v181, v2
	v_mul_f32_e64 v2, |v219|, v183
	v_pk_mul_f32 v[20:21], v[0:1], v[12:13]
	v_pk_add_f32 v[0:1], v[164:165], s[4:5] op_sel_hi:[1,0]
	v_mul_f32_e32 v2, 0x3fb8aa3b, v2
	v_pk_mul_f32 v[16:17], v[0:1], v[16:17]
	v_pk_add_f32 v[0:1], v[166:167], s[4:5] op_sel_hi:[1,0]
	v_exp_f32_e32 v183, v2
	v_div_scale_f32 v2, s[0:1], v193, v193, -v3
	v_pk_mul_f32 v[12:13], v[0:1], v[22:23]
	v_rcp_f32_e32 v22, v2
	v_pk_add_f32 v[0:1], v[178:179], s[4:5] op_sel_hi:[1,0]
	s_or_b32 s0, s14, 3
	v_pk_mul_f32 v[8:9], v[0:1], v[30:31]
	v_fma_f32 v23, -v2, v22, 1.0
	v_pk_add_f32 v[0:1], v[180:181], s[4:5] op_sel_hi:[1,0]
	v_fmac_f32_e32 v22, v23, v22
	v_div_scale_f32 v23, vcc, -v3, v193, -v3
	v_pk_mul_f32 v[4:5], v[0:1], v[26:27]
	v_mul_f32_e32 v26, v23, v22
	v_fma_f32 v27, -v2, v26, v23
	v_fmac_f32_e32 v26, v27, v22
	v_fma_f32 v2, -v2, v26, v23
	v_div_fmas_f32 v2, v2, v22, v26
	v_div_fixup_f32 v23, v2, v193, -v3
	v_mul_f32_e64 v3, |v213|, v23
	v_mul_f32_e32 v3, 0x3fb8aa3b, v3
	v_exp_f32_e32 v22, v3
	v_mul_f32_e64 v3, |v214|, v23
	v_mul_f32_e32 v3, 0x3fb8aa3b, v3
	v_exp_f32_e32 v164, v3
	v_mul_f32_e64 v3, |v215|, v23
	v_mul_f32_e32 v3, 0x3fb8aa3b, v3
	v_exp_f32_e32 v166, v3
	v_mul_f32_e64 v3, |v216|, v23
	v_cvt_f32_i32_e32 v26, s0
	v_pk_add_f32 v[0:1], v[182:183], s[4:5] op_sel_hi:[1,0]
	v_mul_f32_e32 v3, 0x3fb8aa3b, v3
	v_pk_mul_f32 v[0:1], v[0:1], v[176:177]
	v_exp_f32_e32 v176, v3
	v_mul_f32_e64 v3, |v217|, v23
	v_mul_f32_e32 v3, 0x3fb8aa3b, v3
	v_exp_f32_e32 v178, v3
	v_div_scale_f32 v3, s[0:1], v193, v193, -v26
	v_rcp_f32_e32 v27, v3
	v_mul_f32_e64 v30, |v218|, v23
	v_mul_f32_e32 v30, 0x3fb8aa3b, v30
	v_exp_f32_e32 v180, v30
	v_fma_f32 v30, -v3, v27, 1.0
	v_fmac_f32_e32 v27, v30, v27
	v_div_scale_f32 v30, vcc, -v26, v193, -v26
	v_mul_f32_e32 v31, v30, v27
	v_fma_f32 v165, -v3, v31, v30
	v_fmac_f32_e32 v31, v165, v27
	v_fma_f32 v3, -v3, v31, v30
	v_div_fmas_f32 v3, v3, v27, v31
	v_div_fixup_f32 v183, v3, v193, -v26
	v_mul_f32_e64 v2, |v162|, v23
	v_mul_f32_e64 v3, |v162|, v183
	v_mul_f32_e32 v2, 0x3fb8aa3b, v2
	v_mul_f32_e32 v3, 0x3fb8aa3b, v3
	v_exp_f32_e32 v2, v2
	v_exp_f32_e32 v3, v3
	v_mul_f32_e64 v23, |v219|, v23
	v_mul_f32_e32 v23, 0x3fb8aa3b, v23
	v_exp_f32_e32 v182, v23
	v_pk_add_f32 v[2:3], v[2:3], s[4:5] op_sel_hi:[1,0]
	v_mul_f32_e64 v23, |v213|, v183
	v_mul_f32_e32 v23, 0x3fb8aa3b, v23
	v_mul_f32_e64 v26, |v214|, v183
	v_pk_mul_f32 v[30:31], v[2:3], v[6:7]
	v_mul_f32_e64 v6, |v215|, v183
	v_exp_f32_e32 v23, v23
	v_mul_f32_e32 v26, 0x3fb8aa3b, v26
	v_mul_f32_e32 v6, 0x3fb8aa3b, v6
	v_exp_f32_e32 v165, v26
	v_exp_f32_e32 v167, v6
	v_mul_f32_e64 v6, |v216|, v183
	v_mul_f32_e32 v6, 0x3fb8aa3b, v6
	v_exp_f32_e32 v177, v6
	v_pk_add_f32 v[2:3], v[22:23], s[4:5] op_sel_hi:[1,0]
	v_mul_f32_e64 v6, |v217|, v183
	v_pk_mul_f32 v[26:27], v[2:3], v[10:11]
	v_pk_add_f32 v[2:3], v[164:165], s[4:5] op_sel_hi:[1,0]
	v_mul_f32_e32 v6, 0x3fb8aa3b, v6
	v_pk_mul_f32 v[22:23], v[2:3], v[14:15]
	v_pk_add_f32 v[2:3], v[166:167], s[4:5] op_sel_hi:[1,0]
	s_or_b32 s0, s14, 4
	v_pk_mul_f32 v[18:19], v[2:3], v[18:19]
	v_pk_add_f32 v[2:3], v[176:177], s[4:5] op_sel_hi:[1,0]
	v_exp_f32_e32 v179, v6
	v_pk_mul_f32 v[14:15], v[2:3], v[58:59]
	v_cvt_f32_i32_e32 v58, s0
	v_mul_f32_e64 v6, |v218|, v183
	v_mul_f32_e32 v6, 0x3fb8aa3b, v6
	v_exp_f32_e32 v181, v6
	v_pk_add_f32 v[2:3], v[178:179], s[4:5] op_sel_hi:[1,0]
	v_div_scale_f32 v59, s[0:1], v193, v193, -v58
	v_pk_mul_f32 v[10:11], v[2:3], v[62:63]
	v_rcp_f32_e32 v62, v59
	v_mul_f32_e64 v6, |v219|, v183
	v_pk_add_f32 v[2:3], v[180:181], s[4:5] op_sel_hi:[1,0]
	v_mul_f32_e32 v6, 0x3fb8aa3b, v6
	v_exp_f32_e32 v183, v6
	v_pk_mul_f32 v[6:7], v[2:3], v[60:61]
	v_fma_f32 v60, -v59, v62, 1.0
	v_fmac_f32_e32 v62, v60, v62
	v_div_scale_f32 v60, vcc, -v58, v193, -v58
	v_mul_f32_e32 v61, v60, v62
	v_fma_f32 v63, -v59, v61, v60
	v_fmac_f32_e32 v61, v63, v62
	v_fma_f32 v59, -v59, v61, v60
	v_div_fmas_f32 v59, v59, v62, v61
	v_div_fixup_f32 v59, v59, v193, -v58
	v_mul_f32_e64 v60, |v213|, v59
	v_mul_f32_e32 v60, 0x3fb8aa3b, v60
	v_exp_f32_e32 v62, v60
	v_mul_f32_e64 v60, |v214|, v59
	v_pk_add_f32 v[2:3], v[182:183], s[4:5] op_sel_hi:[1,0]
	v_mul_f32_e32 v60, 0x3fb8aa3b, v60
	v_pk_mul_f32 v[2:3], v[2:3], v[92:93]
	v_exp_f32_e32 v92, v60
	v_mul_f32_e64 v60, |v215|, v59
	v_mul_f32_e32 v60, 0x3fb8aa3b, v60
	v_exp_f32_e32 v164, v60
	v_mul_f32_e64 v60, |v216|, v59
	v_mul_f32_e32 v60, 0x3fb8aa3b, v60
	s_or_b32 s0, s14, 5
	v_exp_f32_e32 v166, v60
	v_mul_f32_e64 v60, |v217|, v59
	v_cvt_f32_i32_e32 v61, s0
	v_mul_f32_e32 v60, 0x3fb8aa3b, v60
	v_exp_f32_e32 v176, v60
	v_mul_f32_e64 v60, |v218|, v59
	v_mul_f32_e32 v60, 0x3fb8aa3b, v60
	v_exp_f32_e32 v180, v60
	v_div_scale_f32 v60, s[0:1], v193, v193, -v61
	v_rcp_f32_e32 v63, v60
	v_mul_f32_e64 v58, |v162|, v59
	v_mul_f32_e64 v59, |v219|, v59
	v_mul_f32_e32 v59, 0x3fb8aa3b, v59
	v_exp_f32_e32 v194, v59
	v_fma_f32 v59, -v60, v63, 1.0
	v_fmac_f32_e32 v63, v59, v63
	v_div_scale_f32 v59, vcc, -v61, v193, -v61
	v_mul_f32_e32 v93, v59, v63
	v_fma_f32 v165, -v60, v93, v59
	v_fmac_f32_e32 v93, v165, v63
	v_fma_f32 v59, -v60, v93, v59
	v_div_fmas_f32 v59, v59, v63, v93
	v_div_fixup_f32 v195, v59, v193, -v61
	v_mul_f32_e64 v59, |v162|, v195
	v_mul_f32_e32 v58, 0x3fb8aa3b, v58
	v_mul_f32_e32 v59, 0x3fb8aa3b, v59
	v_mul_f32_e64 v60, |v213|, v195
	v_exp_f32_e32 v58, v58
	v_exp_f32_e32 v59, v59
	v_mul_f32_e32 v60, 0x3fb8aa3b, v60
	v_exp_f32_e32 v63, v60
	s_or_b32 s0, s14, 6
	v_pk_add_f32 v[58:59], v[58:59], s[4:5] op_sel_hi:[1,0]
	s_nop 0
	v_pk_mul_f32 v[60:61], v[58:59], v[44:45]
	v_pk_add_f32 v[44:45], v[62:63], s[4:5] op_sel_hi:[1,0]
	v_and_b32_e32 v59, 0x7fffffff, v25
	v_pk_mul_f32 v[44:45], v[44:45], v[56:57]
	v_and_b32_e32 v57, 0x7fffffff, v24
	v_and_b32_e32 v56, 0x7fffffff, v28
	v_and_b32_e32 v58, 0x7fffffff, v29
	v_pk_add_f32 v[56:57], v[56:57], v[58:59]
	v_and_b32_e32 v59, 0x7fffffff, v26
	v_and_b32_e32 v58, 0x7fffffff, v30
	v_pk_add_f32 v[56:57], v[56:57], v[58:59]
	v_and_b32_e32 v59, 0x7fffffff, v27
	v_and_b32_e32 v58, 0x7fffffff, v31
	v_pk_add_f32 v[56:57], v[56:57], v[58:59]
	v_and_b32_e32 v59, 0x7fffffff, v44
	v_and_b32_e32 v58, 0x7fffffff, v60
	v_pk_add_f32 v[190:191], v[56:57], v[58:59]
	v_mul_f32_e64 v56, |v214|, v195
	v_mul_f32_e32 v56, 0x3fb8aa3b, v56
	v_exp_f32_e32 v93, v56
	v_mul_f32_e64 v56, |v215|, v195
	v_mul_f32_e32 v56, 0x3fb8aa3b, v56
	v_exp_f32_e32 v165, v56
	v_pk_add_f32 v[56:57], v[92:93], s[4:5] op_sel_hi:[1,0]
	v_and_b32_e32 v59, 0x7fffffff, v17
	v_pk_mul_f32 v[56:57], v[56:57], v[40:41]
	v_pk_add_f32 v[40:41], v[164:165], s[4:5] op_sel_hi:[1,0]
	v_and_b32_e32 v58, 0x7fffffff, v21
	v_pk_mul_f32 v[40:41], v[40:41], v[52:53]
	v_and_b32_e32 v53, 0x7fffffff, v16
	v_and_b32_e32 v52, 0x7fffffff, v20
	v_pk_add_f32 v[52:53], v[52:53], v[58:59]
	v_and_b32_e32 v59, 0x7fffffff, v18
	v_and_b32_e32 v58, 0x7fffffff, v22
	v_pk_add_f32 v[52:53], v[52:53], v[58:59]
	v_and_b32_e32 v59, 0x7fffffff, v19
	v_and_b32_e32 v58, 0x7fffffff, v23
	v_pk_add_f32 v[52:53], v[52:53], v[58:59]
	v_and_b32_e32 v59, 0x7fffffff, v40
	v_and_b32_e32 v58, 0x7fffffff, v56
	v_pk_add_f32 v[188:189], v[52:53], v[58:59]
	v_mul_f32_e64 v52, |v216|, v195
	v_mul_f32_e32 v52, 0x3fb8aa3b, v52
	v_exp_f32_e32 v167, v52
	v_mul_f32_e64 v52, |v217|, v195
	v_mul_f32_e32 v52, 0x3fb8aa3b, v52
	v_exp_f32_e32 v177, v52
	v_pk_add_f32 v[52:53], v[166:167], s[4:5] op_sel_hi:[1,0]
	v_and_b32_e32 v59, 0x7fffffff, v9
	v_pk_mul_f32 v[52:53], v[52:53], v[36:37]
	v_pk_add_f32 v[36:37], v[176:177], s[4:5] op_sel_hi:[1,0]
	v_and_b32_e32 v58, 0x7fffffff, v13
	v_pk_mul_f32 v[36:37], v[36:37], v[48:49]
	v_and_b32_e32 v49, 0x7fffffff, v8
	v_and_b32_e32 v48, 0x7fffffff, v12
	v_pk_add_f32 v[48:49], v[48:49], v[58:59]
	v_and_b32_e32 v59, 0x7fffffff, v10
	v_and_b32_e32 v58, 0x7fffffff, v14
	v_pk_add_f32 v[48:49], v[48:49], v[58:59]
	v_and_b32_e32 v59, 0x7fffffff, v11
	v_and_b32_e32 v58, 0x7fffffff, v15
	v_pk_add_f32 v[48:49], v[48:49], v[58:59]
	v_and_b32_e32 v59, 0x7fffffff, v36
	v_and_b32_e32 v58, 0x7fffffff, v52
	v_pk_add_f32 v[184:185], v[48:49], v[58:59]
	v_mul_f32_e64 v48, |v218|, v195
	v_mul_f32_e32 v48, 0x3fb8aa3b, v48
	v_exp_f32_e32 v181, v48
	v_mul_f32_e64 v48, |v219|, v195
	v_mul_f32_e32 v48, 0x3fb8aa3b, v48
	v_exp_f32_e32 v195, v48
	v_cvt_f32_i32_e32 v62, s0
	v_pk_add_f32 v[48:49], v[180:181], s[4:5] op_sel_hi:[1,0]
	v_and_b32_e32 v59, 0x7fffffff, v1
	v_pk_mul_f32 v[48:49], v[48:49], v[32:33]
	v_pk_add_f32 v[32:33], v[194:195], s[4:5] op_sel_hi:[1,0]
	v_div_scale_f32 v63, s[0:1], v193, v193, -v62
	v_pk_mul_f32 v[32:33], v[32:33], v[46:47]
	v_and_b32_e32 v47, 0x7fffffff, v0
	v_and_b32_e32 v46, 0x7fffffff, v4
	v_and_b32_e32 v58, 0x7fffffff, v5
	v_rcp_f32_e32 v92, v63
	v_pk_add_f32 v[46:47], v[46:47], v[58:59]
	v_and_b32_e32 v59, 0x7fffffff, v2
	v_and_b32_e32 v58, 0x7fffffff, v6
	v_pk_add_f32 v[46:47], v[46:47], v[58:59]
	v_and_b32_e32 v59, 0x7fffffff, v3
	v_and_b32_e32 v58, 0x7fffffff, v7
	v_pk_add_f32 v[46:47], v[46:47], v[58:59]
	v_and_b32_e32 v59, 0x7fffffff, v32
	v_and_b32_e32 v58, 0x7fffffff, v48
	v_pk_add_f32 v[180:181], v[46:47], v[58:59]
	v_fma_f32 v46, -v63, v92, 1.0
	v_fmac_f32_e32 v92, v46, v92
	v_div_scale_f32 v46, vcc, -v62, v193, -v62
	v_mul_f32_e32 v47, v46, v92
	v_fma_f32 v58, -v63, v47, v46
	v_fmac_f32_e32 v47, v58, v92
	v_fma_f32 v46, -v63, v47, v46
	v_div_fmas_f32 v46, v46, v92, v47
	v_div_fixup_f32 v59, v46, v193, -v62
	v_mul_f32_e64 v47, |v213|, v59
	v_mul_f32_e32 v47, 0x3fb8aa3b, v47
	v_exp_f32_e32 v58, v47
	v_mul_f32_e64 v47, |v214|, v59
	v_mul_f32_e32 v47, 0x3fb8aa3b, v47
	v_exp_f32_e32 v92, v47
	v_mul_f32_e64 v47, |v215|, v59
	v_mul_f32_e32 v47, 0x3fb8aa3b, v47
	s_or_b32 s0, s14, 7
	v_exp_f32_e32 v164, v47
	v_mul_f32_e64 v47, |v216|, v59
	v_cvt_f32_i32_e32 v62, s0
	v_mul_f32_e32 v47, 0x3fb8aa3b, v47
	v_exp_f32_e32 v166, v47
	v_mul_f32_e64 v47, |v217|, v59
	v_mul_f32_e32 v47, 0x3fb8aa3b, v47
	v_exp_f32_e32 v194, v47
	v_div_scale_f32 v47, s[0:1], v193, v193, -v62
	v_rcp_f32_e32 v63, v47
	v_mul_f32_e64 v93, |v218|, v59
	v_mul_f32_e32 v93, 0x3fb8aa3b, v93
	v_exp_f32_e32 v222, v93
	v_fma_f32 v93, -v47, v63, 1.0
	v_fmac_f32_e32 v63, v93, v63
	v_div_scale_f32 v93, vcc, -v62, v193, -v62
	v_mul_f32_e32 v165, v93, v63
	v_fma_f32 v167, -v47, v165, v93
	v_fmac_f32_e32 v165, v167, v63
	v_fma_f32 v47, -v47, v165, v93
	v_div_fmas_f32 v47, v47, v63, v165
	v_mul_f32_e64 v46, |v162|, v59
	v_div_fixup_f32 v201, v47, v193, -v62
	v_mul_f32_e64 v59, |v219|, v59
	v_mul_f32_e64 v47, |v162|, v201
	v_mul_f32_e32 v59, 0x3fb8aa3b, v59
	v_mul_f32_e32 v46, 0x3fb8aa3b, v46
	v_mul_f32_e32 v47, 0x3fb8aa3b, v47
	v_exp_f32_e32 v224, v59
	v_mul_f32_e64 v59, |v213|, v201
	v_exp_f32_e32 v46, v46
	v_exp_f32_e32 v47, v47
	v_mul_f32_e32 v59, 0x3fb8aa3b, v59
	v_exp_f32_e32 v59, v59
	v_mul_f32_e64 v62, |v214|, v201
	v_pk_add_f32 v[46:47], v[46:47], s[4:5] op_sel_hi:[1,0]
	v_mul_f32_e32 v62, 0x3fb8aa3b, v62
	v_exp_f32_e32 v93, v62
	v_pk_mul_f32 v[62:63], v[46:47], v[34:35]
	v_pk_add_f32 v[34:35], v[58:59], s[4:5] op_sel_hi:[1,0]
	s_or_b32 s0, s14, 8
	v_pk_mul_f32 v[46:47], v[34:35], v[38:39]
	v_mul_f32_e64 v38, |v215|, v201
	v_mul_f32_e32 v38, 0x3fb8aa3b, v38
	v_exp_f32_e32 v165, v38
	v_mul_f32_e64 v38, |v216|, v201
	v_mul_f32_e32 v38, 0x3fb8aa3b, v38
	v_exp_f32_e32 v167, v38
	v_mul_f32_e64 v38, |v217|, v201
	v_mul_f32_e32 v38, 0x3fb8aa3b, v38
	v_exp_f32_e32 v195, v38
	v_pk_add_f32 v[34:35], v[92:93], s[4:5] op_sel_hi:[1,0]
	v_mul_f32_e64 v38, |v218|, v201
	v_pk_mul_f32 v[58:59], v[34:35], v[42:43]
	v_pk_add_f32 v[34:35], v[164:165], s[4:5] op_sel_hi:[1,0]
	v_mul_f32_e32 v38, 0x3fb8aa3b, v38
	v_pk_mul_f32 v[42:43], v[34:35], v[50:51]
	v_pk_add_f32 v[34:35], v[166:167], s[4:5] op_sel_hi:[1,0]
	v_exp_f32_e32 v223, v38
	v_pk_mul_f32 v[54:55], v[34:35], v[54:55]
	v_pk_add_f32 v[34:35], v[194:195], s[4:5] op_sel_hi:[1,0]
	v_mul_f32_e64 v50, |v219|, v201
	v_pk_mul_f32 v[38:39], v[34:35], v[84:85]
	v_cvt_f32_i32_e32 v84, s0
	v_mul_f32_e32 v50, 0x3fb8aa3b, v50
	v_exp_f32_e32 v225, v50
	v_pk_add_f32 v[34:35], v[222:223], s[4:5] op_sel_hi:[1,0]
	v_div_scale_f32 v85, s[0:1], v193, v193, -v84
	v_rcp_f32_e32 v92, v85
	v_pk_mul_f32 v[50:51], v[34:35], v[80:81]
	v_pk_add_f32 v[34:35], v[224:225], s[4:5] op_sel_hi:[1,0]
	s_or_b32 s0, s14, 9
	v_fma_f32 v80, -v85, v92, 1.0
	v_fmac_f32_e32 v92, v80, v92
	v_div_scale_f32 v80, vcc, -v84, v193, -v84
	v_mul_f32_e32 v81, v80, v92
	v_pk_mul_f32 v[34:35], v[34:35], v[88:89]
	v_fma_f32 v88, -v85, v81, v80
	v_fmac_f32_e32 v81, v88, v92
	v_fma_f32 v80, -v85, v81, v80
	v_div_fmas_f32 v80, v80, v92, v81
	v_div_fixup_f32 v85, v80, v193, -v84
	v_mul_f32_e64 v81, |v213|, v85
	v_mul_f32_e32 v81, 0x3fb8aa3b, v81
	v_exp_f32_e32 v84, v81
	v_mul_f32_e64 v81, |v214|, v85
	v_mul_f32_e32 v81, 0x3fb8aa3b, v81
	v_exp_f32_e32 v164, v81
	v_mul_f32_e64 v81, |v215|, v85
	v_mul_f32_e32 v81, 0x3fb8aa3b, v81
	v_exp_f32_e32 v166, v81
	v_mul_f32_e64 v81, |v216|, v85
	v_cvt_f32_i32_e32 v88, s0
	v_mul_f32_e32 v81, 0x3fb8aa3b, v81
	v_exp_f32_e32 v194, v81
	v_mul_f32_e64 v81, |v217|, v85
	v_mul_f32_e32 v81, 0x3fb8aa3b, v81
	v_exp_f32_e32 v222, v81
	v_div_scale_f32 v81, s[0:1], v193, v193, -v88
	v_rcp_f32_e32 v89, v81
	v_mul_f32_e64 v92, |v218|, v85
	v_mul_f32_e32 v92, 0x3fb8aa3b, v92
	v_exp_f32_e32 v224, v92
	v_fma_f32 v92, -v81, v89, 1.0
	v_fmac_f32_e32 v89, v92, v89
	v_div_scale_f32 v92, vcc, -v88, v193, -v88
	v_mul_f32_e32 v93, v92, v89
	v_fma_f32 v165, -v81, v93, v92
	v_fmac_f32_e32 v93, v165, v89
	v_fma_f32 v81, -v81, v93, v92
	v_div_fmas_f32 v81, v81, v89, v93
	v_mul_f32_e64 v80, |v162|, v85
	v_div_fixup_f32 v201, v81, v193, -v88
	v_mul_f32_e64 v85, |v219|, v85
	v_mul_f32_e64 v81, |v162|, v201
	v_mul_f32_e32 v85, 0x3fb8aa3b, v85
	v_mul_f32_e32 v80, 0x3fb8aa3b, v80
	v_mul_f32_e32 v81, 0x3fb8aa3b, v81
	v_exp_f32_e32 v226, v85
	v_mul_f32_e64 v85, |v213|, v201
	v_exp_f32_e32 v80, v80
	v_exp_f32_e32 v81, v81
	v_mul_f32_e32 v85, 0x3fb8aa3b, v85
	v_exp_f32_e32 v85, v85
	v_mul_f32_e64 v88, |v214|, v201
	v_pk_add_f32 v[80:81], v[80:81], s[4:5] op_sel_hi:[1,0]
	v_mul_f32_e32 v88, 0x3fb8aa3b, v88
	v_pk_mul_f32 v[92:93], v[80:81], v[64:65]
	v_pk_add_f32 v[64:65], v[84:85], s[4:5] op_sel_hi:[1,0]
	v_exp_f32_e32 v165, v88
	v_pk_mul_f32 v[88:89], v[64:65], v[68:69]
	v_mul_f32_e64 v68, |v215|, v201
	v_mul_f32_e32 v68, 0x3fb8aa3b, v68
	v_exp_f32_e32 v167, v68
	v_mul_f32_e64 v68, |v216|, v201
	v_mul_f32_e32 v68, 0x3fb8aa3b, v68
	v_exp_f32_e32 v195, v68
	v_pk_add_f32 v[64:65], v[164:165], s[4:5] op_sel_hi:[1,0]
	v_mul_f32_e64 v68, |v217|, v201
	v_pk_mul_f32 v[84:85], v[64:65], v[72:73]
	v_pk_add_f32 v[64:65], v[166:167], s[4:5] op_sel_hi:[1,0]
	v_mul_f32_e32 v68, 0x3fb8aa3b, v68
	v_pk_mul_f32 v[80:81], v[64:65], v[76:77]
	v_pk_add_f32 v[64:65], v[194:195], s[4:5] op_sel_hi:[1,0]
	s_or_b32 s0, s14, 10
	v_exp_f32_e32 v223, v68
	v_pk_mul_f32 v[76:77], v[64:65], v[82:83]
	v_cvt_f32_i32_e32 v82, s0
	v_mul_f32_e64 v68, |v218|, v201
	v_mul_f32_e32 v68, 0x3fb8aa3b, v68
	v_exp_f32_e32 v225, v68
	v_pk_add_f32 v[64:65], v[222:223], s[4:5] op_sel_hi:[1,0]
	v_div_scale_f32 v83, s[0:1], v193, v193, -v82
	v_pk_mul_f32 v[72:73], v[64:65], v[90:91]
	v_rcp_f32_e32 v90, v83
	v_mul_f32_e64 v68, |v219|, v201
	v_pk_add_f32 v[64:65], v[224:225], s[4:5] op_sel_hi:[1,0]
	v_mul_f32_e32 v68, 0x3fb8aa3b, v68
	v_exp_f32_e32 v227, v68
	v_pk_mul_f32 v[68:69], v[64:65], v[86:87]
	v_fma_f32 v86, -v83, v90, 1.0
	v_fmac_f32_e32 v90, v86, v90
	v_div_scale_f32 v86, vcc, -v82, v193, -v82
	v_mul_f32_e32 v87, v86, v90
	v_fma_f32 v91, -v83, v87, v86
	v_fmac_f32_e32 v87, v91, v90
	v_fma_f32 v83, -v83, v87, v86
	v_div_fmas_f32 v83, v83, v90, v87
	v_div_fixup_f32 v87, v83, v193, -v82
	v_mul_f32_e64 v83, |v213|, v87
	v_mul_f32_e32 v83, 0x3fb8aa3b, v83
	v_exp_f32_e32 v86, v83
	v_mul_f32_e64 v83, |v214|, v87
	v_mul_f32_e32 v83, 0x3fb8aa3b, v83
	v_exp_f32_e32 v164, v83
	v_mul_f32_e64 v83, |v215|, v87
	v_mul_f32_e32 v83, 0x3fb8aa3b, v83
	s_or_b32 s0, s14, 11
	v_exp_f32_e32 v166, v83
	v_mul_f32_e64 v83, |v216|, v87
	v_cvt_f32_i32_e32 v90, s0
	v_mul_f32_e32 v83, 0x3fb8aa3b, v83
	v_exp_f32_e32 v194, v83
	v_mul_f32_e64 v83, |v217|, v87
	v_mul_f32_e32 v83, 0x3fb8aa3b, v83
	v_exp_f32_e32 v222, v83
	v_div_scale_f32 v83, s[0:1], v193, v193, -v90
	v_rcp_f32_e32 v91, v83
	v_pk_add_f32 v[64:65], v[226:227], s[4:5] op_sel_hi:[1,0]
	v_mul_f32_e64 v82, |v162|, v87
	v_pk_mul_f32 v[64:65], v[64:65], v[94:95]
	v_mul_f32_e64 v94, |v218|, v87
	v_mul_f32_e32 v94, 0x3fb8aa3b, v94
	v_exp_f32_e32 v224, v94
	v_fma_f32 v94, -v83, v91, 1.0
	v_fmac_f32_e32 v91, v94, v91
	v_div_scale_f32 v94, vcc, -v90, v193, -v90
	v_mul_f32_e32 v95, v94, v91
	v_fma_f32 v165, -v83, v95, v94
	v_fmac_f32_e32 v95, v165, v91
	v_fma_f32 v83, -v83, v95, v94
	v_div_fmas_f32 v83, v83, v91, v95
	v_div_fixup_f32 v201, v83, v193, -v90
	v_mul_f32_e64 v87, |v219|, v87
	v_mul_f32_e64 v83, |v162|, v201
	v_mul_f32_e32 v87, 0x3fb8aa3b, v87
	v_mul_f32_e32 v82, 0x3fb8aa3b, v82
	v_mul_f32_e32 v83, 0x3fb8aa3b, v83
	v_exp_f32_e32 v226, v87
	v_mul_f32_e64 v87, |v213|, v201
	v_exp_f32_e32 v82, v82
	v_exp_f32_e32 v83, v83
	v_mul_f32_e32 v87, 0x3fb8aa3b, v87
	v_exp_f32_e32 v87, v87
	v_mul_f32_e64 v90, |v214|, v201
	v_pk_add_f32 v[82:83], v[82:83], s[4:5] op_sel_hi:[1,0]
	v_mul_f32_e32 v90, 0x3fb8aa3b, v90
	v_pk_mul_f32 v[94:95], v[82:83], v[66:67]
	v_pk_add_f32 v[66:67], v[86:87], s[4:5] op_sel_hi:[1,0]
	v_exp_f32_e32 v165, v90
	v_pk_mul_f32 v[90:91], v[66:67], v[70:71]
	v_mul_f32_e64 v70, |v215|, v201
	v_mul_f32_e32 v70, 0x3fb8aa3b, v70
	v_exp_f32_e32 v167, v70
	v_mul_f32_e64 v70, |v216|, v201
	v_mul_f32_e32 v70, 0x3fb8aa3b, v70
	v_exp_f32_e32 v195, v70
	v_pk_add_f32 v[66:67], v[164:165], s[4:5] op_sel_hi:[1,0]
	v_mul_f32_e64 v70, |v217|, v201
	v_pk_mul_f32 v[86:87], v[66:67], v[74:75]
	v_pk_add_f32 v[66:67], v[166:167], s[4:5] op_sel_hi:[1,0]
	v_mul_f32_e32 v70, 0x3fb8aa3b, v70
	v_pk_mul_f32 v[82:83], v[66:67], v[78:79]
	v_pk_add_f32 v[66:67], v[194:195], s[4:5] op_sel_hi:[1,0]
	s_or_b32 s0, s14, 12
	v_exp_f32_e32 v223, v70
	v_pk_mul_f32 v[78:79], v[66:67], v[114:115]
	v_cvt_f32_i32_e32 v114, s0
	v_mul_f32_e64 v70, |v218|, v201
	v_mul_f32_e32 v70, 0x3fb8aa3b, v70
	v_exp_f32_e32 v225, v70
	v_pk_add_f32 v[66:67], v[222:223], s[4:5] op_sel_hi:[1,0]
	v_div_scale_f32 v115, s[0:1], v193, v193, -v114
	v_pk_mul_f32 v[74:75], v[66:67], v[122:123]
	v_rcp_f32_e32 v122, v115
	v_mul_f32_e64 v70, |v219|, v201
	v_pk_add_f32 v[66:67], v[224:225], s[4:5] op_sel_hi:[1,0]
	v_mul_f32_e32 v70, 0x3fb8aa3b, v70
	v_exp_f32_e32 v227, v70
	v_pk_mul_f32 v[70:71], v[66:67], v[118:119]
	v_fma_f32 v118, -v115, v122, 1.0
	v_fmac_f32_e32 v122, v118, v122
	v_div_scale_f32 v118, vcc, -v114, v193, -v114
	v_mul_f32_e32 v119, v118, v122
	v_fma_f32 v123, -v115, v119, v118
	v_fmac_f32_e32 v119, v123, v122
	v_fma_f32 v115, -v115, v119, v118
	v_div_fmas_f32 v115, v115, v122, v119
	v_div_fixup_f32 v119, v115, v193, -v114
	v_mul_f32_e64 v115, |v213|, v119
	v_mul_f32_e32 v115, 0x3fb8aa3b, v115
	v_exp_f32_e32 v118, v115
	v_mul_f32_e64 v115, |v214|, v119
	v_mul_f32_e32 v115, 0x3fb8aa3b, v115
	v_exp_f32_e32 v164, v115
	v_mul_f32_e64 v115, |v215|, v119
	v_mul_f32_e32 v115, 0x3fb8aa3b, v115
	s_or_b32 s0, s14, 13
	v_exp_f32_e32 v166, v115
	v_mul_f32_e64 v115, |v216|, v119
	v_cvt_f32_i32_e32 v122, s0
	v_mul_f32_e32 v115, 0x3fb8aa3b, v115
	v_exp_f32_e32 v194, v115
	v_mul_f32_e64 v115, |v217|, v119
	v_mul_f32_e32 v115, 0x3fb8aa3b, v115
	v_exp_f32_e32 v222, v115
	v_div_scale_f32 v115, s[0:1], v193, v193, -v122
	v_rcp_f32_e32 v123, v115
	v_pk_add_f32 v[66:67], v[226:227], s[4:5] op_sel_hi:[1,0]
	v_mul_f32_e64 v114, |v162|, v119
	v_pk_mul_f32 v[66:67], v[66:67], v[126:127]
	v_mul_f32_e64 v126, |v218|, v119
	v_mul_f32_e32 v126, 0x3fb8aa3b, v126
	v_exp_f32_e32 v224, v126
	v_fma_f32 v126, -v115, v123, 1.0
	v_fmac_f32_e32 v123, v126, v123
	v_div_scale_f32 v126, vcc, -v122, v193, -v122
	v_mul_f32_e32 v127, v126, v123
	v_fma_f32 v165, -v115, v127, v126
	v_fmac_f32_e32 v127, v165, v123
	v_fma_f32 v115, -v115, v127, v126
	v_div_fmas_f32 v115, v115, v123, v127
	v_div_fixup_f32 v201, v115, v193, -v122
	v_mul_f32_e64 v119, |v219|, v119
	v_mul_f32_e64 v115, |v162|, v201
	v_mul_f32_e32 v119, 0x3fb8aa3b, v119
	v_mul_f32_e32 v114, 0x3fb8aa3b, v114
	v_mul_f32_e32 v115, 0x3fb8aa3b, v115
	v_exp_f32_e32 v226, v119
	v_mul_f32_e64 v119, |v213|, v201
	v_exp_f32_e32 v114, v114
	v_exp_f32_e32 v115, v115
	v_mul_f32_e32 v119, 0x3fb8aa3b, v119
	v_exp_f32_e32 v119, v119
	v_mul_f32_e64 v122, |v214|, v201
	v_pk_add_f32 v[114:115], v[114:115], s[4:5] op_sel_hi:[1,0]
	v_mul_f32_e32 v122, 0x3fb8aa3b, v122
	v_pk_mul_f32 v[126:127], v[114:115], v[96:97]
	v_pk_add_f32 v[96:97], v[118:119], s[4:5] op_sel_hi:[1,0]
	v_exp_f32_e32 v165, v122
	v_pk_mul_f32 v[122:123], v[96:97], v[100:101]
	v_mul_f32_e64 v100, |v215|, v201
	v_mul_f32_e32 v100, 0x3fb8aa3b, v100
	v_exp_f32_e32 v167, v100
	v_mul_f32_e64 v100, |v216|, v201
	v_mul_f32_e32 v100, 0x3fb8aa3b, v100
	v_exp_f32_e32 v195, v100
	v_pk_add_f32 v[96:97], v[164:165], s[4:5] op_sel_hi:[1,0]
	v_mul_f32_e64 v100, |v217|, v201
	v_pk_mul_f32 v[118:119], v[96:97], v[104:105]
	v_pk_add_f32 v[96:97], v[166:167], s[4:5] op_sel_hi:[1,0]
	v_mul_f32_e32 v100, 0x3fb8aa3b, v100
	v_pk_mul_f32 v[114:115], v[96:97], v[108:109]
	v_pk_add_f32 v[96:97], v[194:195], s[4:5] op_sel_hi:[1,0]
	s_or_b32 s0, s14, 14
	v_exp_f32_e32 v223, v100
	v_pk_mul_f32 v[108:109], v[96:97], v[128:129]
	v_cvt_f32_i32_e32 v128, s0
	v_mul_f32_e64 v100, |v218|, v201
	v_mul_f32_e32 v100, 0x3fb8aa3b, v100
	v_exp_f32_e32 v225, v100
	v_pk_add_f32 v[96:97], v[222:223], s[4:5] op_sel_hi:[1,0]
	v_div_scale_f32 v129, s[0:1], v193, v193, -v128
	v_pk_mul_f32 v[104:105], v[96:97], v[132:133]
	v_rcp_f32_e32 v132, v129
	v_mul_f32_e64 v100, |v219|, v201
	v_pk_add_f32 v[96:97], v[224:225], s[4:5] op_sel_hi:[1,0]
	v_mul_f32_e32 v100, 0x3fb8aa3b, v100
	v_exp_f32_e32 v227, v100
	v_pk_mul_f32 v[100:101], v[96:97], v[130:131]
	v_fma_f32 v130, -v129, v132, 1.0
	v_fmac_f32_e32 v132, v130, v132
	v_div_scale_f32 v130, vcc, -v128, v193, -v128
	v_mul_f32_e32 v131, v130, v132
	v_fma_f32 v133, -v129, v131, v130
	v_fmac_f32_e32 v131, v133, v132
	v_fma_f32 v129, -v129, v131, v130
	v_div_fmas_f32 v129, v129, v132, v131
	v_div_fixup_f32 v129, v129, v193, -v128
	v_mul_f32_e64 v131, |v214|, v129
	v_mul_f32_e32 v131, 0x3fb8aa3b, v131
	v_exp_f32_e32 v132, v131
	v_mul_f32_e64 v131, |v215|, v129
	v_pk_add_f32 v[96:97], v[226:227], s[4:5] op_sel_hi:[1,0]
	v_mul_f32_e32 v131, 0x3fb8aa3b, v131
	v_pk_mul_f32 v[96:97], v[96:97], v[134:135]
	v_exp_f32_e32 v134, v131
	v_mul_f32_e64 v131, |v216|, v129
	v_mul_f32_e32 v131, 0x3fb8aa3b, v131
	v_exp_f32_e32 v164, v131
	v_mul_f32_e64 v131, |v217|, v129
	v_mul_f32_e32 v131, 0x3fb8aa3b, v131
	s_or_b32 s0, s14, 15
	v_exp_f32_e32 v166, v131
	v_cvt_f32_i32_e32 v131, s0
	v_mul_f32_e64 v133, |v218|, v129
	v_mul_f32_e64 v128, |v162|, v129
	v_mul_f32_e64 v130, |v213|, v129
	v_div_scale_f32 v135, s[0:1], v193, v193, -v131
	v_rcp_f32_e32 v165, v135
	v_mul_f32_e32 v133, 0x3fb8aa3b, v133
	v_mul_f32_e64 v129, |v219|, v129
	v_exp_f32_e32 v194, v133
	v_mul_f32_e32 v133, 0x3fb8aa3b, v129
	v_fma_f32 v129, -v135, v165, 1.0
	v_fmac_f32_e32 v165, v129, v165
	v_div_scale_f32 v129, vcc, -v131, v193, -v131
	v_mul_f32_e32 v167, v129, v165
	v_fma_f32 v195, -v135, v167, v129
	v_fmac_f32_e32 v167, v195, v165
	v_fma_f32 v129, -v135, v167, v129
	v_div_fmas_f32 v129, v129, v165, v167
	v_div_fixup_f32 v193, v129, v193, -v131
	v_mul_f32_e64 v129, |v162|, v193
	v_mul_f32_e32 v128, 0x3fb8aa3b, v128
	v_mul_f32_e32 v129, 0x3fb8aa3b, v129
	v_mul_f32_e64 v131, |v213|, v193
	v_exp_f32_e32 v128, v128
	v_mul_f32_e32 v130, 0x3fb8aa3b, v130
	v_exp_f32_e32 v129, v129
	v_mul_f32_e32 v131, 0x3fb8aa3b, v131
	v_exp_f32_e32 v130, v130
	v_exp_f32_e32 v131, v131
	v_pk_add_f32 v[128:129], v[128:129], s[4:5] op_sel_hi:[1,0]
	v_and_b32_e32 v186, 0x7fffffff, v61
	v_and_b32_e32 v187, 0x7fffffff, v45
	v_pk_mul_f32 v[128:129], v[128:129], v[120:121]
	v_pk_add_f32 v[120:121], v[130:131], s[4:5] op_sel_hi:[1,0]
	v_and_b32_e32 v131, 0x7fffffff, v46
	v_pk_mul_f32 v[124:125], v[120:121], v[124:125]
	v_pk_add_f32 v[120:121], v[190:191], v[186:187]
	v_and_b32_e32 v130, 0x7fffffff, v62
	v_pk_add_f32 v[120:121], v[120:121], v[130:131]
	v_and_b32_e32 v131, 0x7fffffff, v47
	v_and_b32_e32 v130, 0x7fffffff, v63
	v_pk_add_f32 v[120:121], v[120:121], v[130:131]
	v_and_b32_e32 v131, 0x7fffffff, v88
	v_and_b32_e32 v130, 0x7fffffff, v92
	v_pk_add_f32 v[120:121], v[120:121], v[130:131]
	v_and_b32_e32 v131, 0x7fffffff, v89
	v_and_b32_e32 v130, 0x7fffffff, v93
	v_exp_f32_e32 v222, v133
	v_pk_add_f32 v[120:121], v[120:121], v[130:131]
	v_and_b32_e32 v131, 0x7fffffff, v90
	v_and_b32_e32 v130, 0x7fffffff, v94
	v_mul_f32_e64 v133, |v214|, v193
	v_pk_add_f32 v[120:121], v[120:121], v[130:131]
	v_and_b32_e32 v131, 0x7fffffff, v91
	v_and_b32_e32 v130, 0x7fffffff, v95
	v_mul_f32_e32 v133, 0x3fb8aa3b, v133
	v_mul_f32_e64 v135, |v215|, v193
	v_pk_add_f32 v[120:121], v[120:121], v[130:131]
	v_and_b32_e32 v131, 0x7fffffff, v122
	v_and_b32_e32 v130, 0x7fffffff, v126
	v_exp_f32_e32 v133, v133
	v_mul_f32_e32 v135, 0x3fb8aa3b, v135
	v_pk_add_f32 v[120:121], v[120:121], v[130:131]
	v_and_b32_e32 v131, 0x7fffffff, v123
	v_and_b32_e32 v130, 0x7fffffff, v127
	v_exp_f32_e32 v135, v135
	v_pk_add_f32 v[120:121], v[120:121], v[130:131]
	v_and_b32_e32 v131, 0x7fffffff, v124
	v_and_b32_e32 v130, 0x7fffffff, v128
	v_pk_add_f32 v[120:121], v[120:121], v[130:131]
	v_and_b32_e32 v131, 0x7fffffff, v125
	v_and_b32_e32 v130, 0x7fffffff, v129
	v_pk_add_f32 v[130:131], v[120:121], v[130:131]
	v_pk_add_f32 v[120:121], v[132:133], s[4:5] op_sel_hi:[1,0]
	v_and_b32_e32 v182, 0x7fffffff, v57
	v_and_b32_e32 v183, 0x7fffffff, v41
	v_pk_mul_f32 v[120:121], v[120:121], v[110:111]
	v_pk_add_f32 v[110:111], v[134:135], s[4:5] op_sel_hi:[1,0]
	v_and_b32_e32 v133, 0x7fffffff, v42
	v_pk_mul_f32 v[116:117], v[110:111], v[116:117]
	v_pk_add_f32 v[110:111], v[188:189], v[182:183]
	v_and_b32_e32 v132, 0x7fffffff, v58
	v_pk_add_f32 v[110:111], v[110:111], v[132:133]
	v_and_b32_e32 v133, 0x7fffffff, v43
	v_and_b32_e32 v132, 0x7fffffff, v59
	v_pk_add_f32 v[110:111], v[110:111], v[132:133]
	v_and_b32_e32 v133, 0x7fffffff, v80
	v_and_b32_e32 v132, 0x7fffffff, v84
	v_pk_add_f32 v[110:111], v[110:111], v[132:133]
	v_and_b32_e32 v133, 0x7fffffff, v81
	v_and_b32_e32 v132, 0x7fffffff, v85
	v_mul_f32_e64 v134, |v216|, v193
	v_pk_add_f32 v[110:111], v[110:111], v[132:133]
	v_and_b32_e32 v133, 0x7fffffff, v82
	v_and_b32_e32 v132, 0x7fffffff, v86
	v_mul_f32_e32 v134, 0x3fb8aa3b, v134
	v_pk_add_f32 v[110:111], v[110:111], v[132:133]
	v_and_b32_e32 v133, 0x7fffffff, v83
	v_and_b32_e32 v132, 0x7fffffff, v87
	v_exp_f32_e32 v165, v134
	v_mul_f32_e64 v134, |v217|, v193
	v_pk_add_f32 v[110:111], v[110:111], v[132:133]
	v_and_b32_e32 v133, 0x7fffffff, v114
	v_and_b32_e32 v132, 0x7fffffff, v118
	v_mul_f32_e32 v134, 0x3fb8aa3b, v134
	v_pk_add_f32 v[110:111], v[110:111], v[132:133]
	v_and_b32_e32 v133, 0x7fffffff, v115
	v_and_b32_e32 v132, 0x7fffffff, v119
	v_exp_f32_e32 v167, v134
	v_pk_add_f32 v[110:111], v[110:111], v[132:133]
	v_and_b32_e32 v133, 0x7fffffff, v116
	v_and_b32_e32 v132, 0x7fffffff, v120
	v_pk_add_f32 v[110:111], v[110:111], v[132:133]
	v_and_b32_e32 v133, 0x7fffffff, v117
	v_and_b32_e32 v132, 0x7fffffff, v121
	v_pk_add_f32 v[132:133], v[110:111], v[132:133]
	v_pk_add_f32 v[110:111], v[164:165], s[4:5] op_sel_hi:[1,0]
	v_and_b32_e32 v178, 0x7fffffff, v53
	v_and_b32_e32 v179, 0x7fffffff, v37
	v_pk_mul_f32 v[110:111], v[110:111], v[102:103]
	v_pk_add_f32 v[102:103], v[166:167], s[4:5] op_sel_hi:[1,0]
	v_and_b32_e32 v135, 0x7fffffff, v38
	v_pk_mul_f32 v[106:107], v[102:103], v[106:107]
	v_pk_add_f32 v[102:103], v[184:185], v[178:179]
	v_and_b32_e32 v134, 0x7fffffff, v54
	v_pk_add_f32 v[102:103], v[102:103], v[134:135]
	v_and_b32_e32 v135, 0x7fffffff, v39
	v_and_b32_e32 v134, 0x7fffffff, v55
	v_pk_add_f32 v[102:103], v[102:103], v[134:135]
	v_and_b32_e32 v135, 0x7fffffff, v72
	v_and_b32_e32 v134, 0x7fffffff, v76
	v_pk_add_f32 v[102:103], v[102:103], v[134:135]
	v_and_b32_e32 v135, 0x7fffffff, v73
	v_and_b32_e32 v134, 0x7fffffff, v77
	v_mul_f32_e64 v164, |v218|, v193
	v_pk_add_f32 v[102:103], v[102:103], v[134:135]
	v_and_b32_e32 v135, 0x7fffffff, v74
	v_and_b32_e32 v134, 0x7fffffff, v78
	v_mul_f32_e32 v164, 0x3fb8aa3b, v164
	v_pk_add_f32 v[102:103], v[102:103], v[134:135]
	v_and_b32_e32 v135, 0x7fffffff, v75
	v_and_b32_e32 v134, 0x7fffffff, v79
	v_exp_f32_e32 v195, v164
	v_mul_f32_e64 v164, |v219|, v193
	v_pk_add_f32 v[102:103], v[102:103], v[134:135]
	v_and_b32_e32 v135, 0x7fffffff, v104
	v_and_b32_e32 v134, 0x7fffffff, v108
	v_mul_f32_e32 v164, 0x3fb8aa3b, v164
	v_pk_add_f32 v[102:103], v[102:103], v[134:135]
	v_and_b32_e32 v135, 0x7fffffff, v105
	v_and_b32_e32 v134, 0x7fffffff, v109
	v_exp_f32_e32 v223, v164
	v_pk_add_f32 v[102:103], v[102:103], v[134:135]
	v_and_b32_e32 v135, 0x7fffffff, v106
	v_and_b32_e32 v134, 0x7fffffff, v110
	v_pk_add_f32 v[102:103], v[102:103], v[134:135]
	v_and_b32_e32 v135, 0x7fffffff, v107
	v_and_b32_e32 v134, 0x7fffffff, v111
	v_pk_add_f32 v[134:135], v[102:103], v[134:135]
	v_pk_add_f32 v[102:103], v[194:195], s[4:5] op_sel_hi:[1,0]
	v_and_b32_e32 v176, 0x7fffffff, v49
	v_and_b32_e32 v177, 0x7fffffff, v33
	v_pk_mul_f32 v[102:103], v[102:103], v[98:99]
	v_pk_add_f32 v[98:99], v[222:223], s[4:5] op_sel_hi:[1,0]
	v_and_b32_e32 v165, 0x7fffffff, v34
	v_pk_mul_f32 v[98:99], v[98:99], v[136:137]
	v_pk_add_f32 v[136:137], v[180:181], v[176:177]
	v_and_b32_e32 v164, 0x7fffffff, v50
	s_and_b64 s[0:1], s[12:13], exec
	v_pk_add_f32 v[136:137], v[136:137], v[164:165]
	v_and_b32_e32 v165, 0x7fffffff, v35
	v_and_b32_e32 v164, 0x7fffffff, v51
	s_mov_b32 s0, 0x10800000
	v_pk_add_f32 v[136:137], v[136:137], v[164:165]
	v_and_b32_e32 v165, 0x7fffffff, v64
	v_and_b32_e32 v164, 0x7fffffff, v68
	s_cselect_b32 s0, s0, 0x10c00000
	v_pk_add_f32 v[136:137], v[136:137], v[164:165]
	v_and_b32_e32 v165, 0x7fffffff, v65
	v_and_b32_e32 v164, 0x7fffffff, v69
	s_add_u32 s4, s92, s0
	v_pk_add_f32 v[136:137], v[136:137], v[164:165]
	v_and_b32_e32 v165, 0x7fffffff, v66
	v_and_b32_e32 v164, 0x7fffffff, v70
	s_addc_u32 s5, s93, 0
	s_ashr_i32 s15, s14, 31
	v_pk_add_f32 v[136:137], v[136:137], v[164:165]
	v_and_b32_e32 v165, 0x7fffffff, v67
	v_and_b32_e32 v164, 0x7fffffff, v71
	s_lshl_b64 s[0:1], s[14:15], 2
	v_pk_add_f32 v[136:137], v[136:137], v[164:165]
	v_and_b32_e32 v165, 0x7fffffff, v96
	v_and_b32_e32 v164, 0x7fffffff, v100
	s_add_u32 s14, s4, s0
	v_pk_add_f32 v[136:137], v[136:137], v[164:165]
	v_and_b32_e32 v165, 0x7fffffff, v97
	v_and_b32_e32 v164, 0x7fffffff, v101
	s_addc_u32 s15, s5, s1
	v_pk_add_f32 v[136:137], v[136:137], v[164:165]
	v_and_b32_e32 v165, 0x7fffffff, v98
	v_and_b32_e32 v164, 0x7fffffff, v102
	s_and_b64 s[0:1], s[12:13], exec
	v_pk_add_f32 v[136:137], v[136:137], v[164:165]
	v_and_b32_e32 v165, 0x7fffffff, v99
	v_and_b32_e32 v164, 0x7fffffff, v103
	s_cselect_b32 s0, 8, 12
	v_pk_add_f32 v[136:137], v[136:137], v[164:165]
	v_lshlrev_b64 v[164:165], s0, v[138:139]
	v_lshl_add_u64 v[164:165], v[164:165], 2, s[14:15]
	global_store_dwordx4 v[164:165], v[28:31], off
	global_store_dwordx4 v[164:165], v[60:63], off offset:16
	global_store_dwordx4 v[164:165], v[92:95], off offset:32
	global_store_dwordx4 v[164:165], v[126:129], off offset:48
	v_lshlrev_b64 v[28:29], s0, v[148:149]
	v_lshl_add_u64 v[28:29], v[28:29], 2, s[14:15]
	global_store_dwordx4 v[28:29], v[24:27], off
	global_store_dwordx4 v[28:29], v[44:47], off offset:16
	global_store_dwordx4 v[28:29], v[88:91], off offset:32
	global_store_dwordx4 v[28:29], v[122:125], off offset:48
	v_lshlrev_b64 v[24:25], s0, v[150:151]
	v_lshl_add_u64 v[24:25], v[24:25], 2, s[14:15]
	global_store_dwordx4 v[24:25], v[20:23], off
	global_store_dwordx4 v[24:25], v[56:59], off offset:16
	global_store_dwordx4 v[24:25], v[84:87], off offset:32
	global_store_dwordx4 v[24:25], v[118:121], off offset:48
	v_lshlrev_b64 v[20:21], s0, v[152:153]
	v_lshl_add_u64 v[20:21], v[20:21], 2, s[14:15]
	global_store_dwordx4 v[20:21], v[16:19], off
	global_store_dwordx4 v[20:21], v[40:43], off offset:16
	global_store_dwordx4 v[20:21], v[80:83], off offset:32
	global_store_dwordx4 v[20:21], v[114:117], off offset:48
	v_lshlrev_b64 v[16:17], s0, v[154:155]
	v_lshl_add_u64 v[16:17], v[16:17], 2, s[14:15]
	global_store_dwordx4 v[16:17], v[12:15], off
	global_store_dwordx4 v[16:17], v[52:55], off offset:16
	global_store_dwordx4 v[16:17], v[76:79], off offset:32
	global_store_dwordx4 v[16:17], v[108:111], off offset:48
	v_lshlrev_b64 v[12:13], s0, v[156:157]
	v_lshl_add_u64 v[12:13], v[12:13], 2, s[14:15]
	global_store_dwordx4 v[12:13], v[8:11], off
	global_store_dwordx4 v[12:13], v[36:39], off offset:16
	global_store_dwordx4 v[12:13], v[72:75], off offset:32
	global_store_dwordx4 v[12:13], v[104:107], off offset:48
	v_lshlrev_b64 v[8:9], s0, v[158:159]
	v_lshl_add_u64 v[8:9], v[8:9], 2, s[14:15]
	global_store_dwordx4 v[8:9], v[4:7], off
	global_store_dwordx4 v[8:9], v[48:51], off offset:16
	global_store_dwordx4 v[8:9], v[68:71], off offset:32
	global_store_dwordx4 v[8:9], v[100:103], off offset:48
	v_lshlrev_b64 v[4:5], s0, v[160:161]
	s_ashr_i32 s11, s10, 31
	v_lshl_add_u64 v[4:5], v[4:5], 2, s[14:15]
	s_lshl_b64 s[0:1], s[10:11], 14
	s_add_i32 s10, s10, s88
	global_store_dwordx4 v[4:5], v[0:3], off
	global_store_dwordx4 v[4:5], v[32:35], off offset:16
	global_store_dwordx4 v[4:5], v[64:67], off offset:32
	global_store_dwordx4 v[4:5], v[96:99], off offset:48
	v_lshl_add_u64 v[0:1], v[140:141], 0, s[0:1]
	s_cmpk_gt_i32 s10, 0x10f
	global_store_dwordx4 v[0:1], v[130:133], off
	global_store_dwordx4 v[0:1], v[134:137], off offset:16
	s_barrier
	s_cbranch_scc0 .LBB0_936
